# v40 stack + tile scheduler: group size is always 8, runtime division chain (v_rcp + readfirstlane + 25 SALU) replaced by shift and mask in the P3 and P5 unit loops
# baseline (speedup 1.0000x reference)
.LBB0_534:
	s_ashr_i32 s7, s6, 31
	s_lshr_b32 s7, s7, 29
	s_add_i32 s7, s6, s7
	s_ashr_i32 s16, s7, 3
	s_and_b32 s7, s7, -8
	s_sub_i32 s6, s6, s7
	s_cmp_lt_i32 s6, 0
	s_movk_i32 s7, 0xa1
	s_cselect_b32 s7, s7, 0xa0
	s_mul_i32 s6, s6, s7
	s_add_i32 s6, s6, s16
	s_ashr_i32 s7, s6, 31
	s_lshr_b32 s7, s7, 27
	s_add_i32 s7, s6, s7
	s_ashr_i32 s16, s7, 5
	s_lshl_b32 s16, s16, 3
	s_andn2_b32 s7, s7, 31
	s_sub_i32 s6, s6, s7
	s_ashr_i32 s68, s6, 3
	s_and_b32 s6, s6, 7
	s_add_i32 s69, s16, s6

;     __device__ __forceinline__ bool next(int i, Unit& u) const {
;         const int ti = (NSUB == 1) ? i : i / NSUB, sub = (NSUB == 1) ? 0 : i - ti * NSUB;
;         const long L = (long)ti * G + c; if (L >= (long)nM * nN) return false;
;         tile_of((int)L, nM, nN, u.pm, u.pn);
.LBB0_895:
	s_add_i32 s13, s13, 1
	s_mul_i32 s4, s13, s29
	s_mul_hi_u32 s5, s13, s28
	s_add_i32 s5, s5, s4
	s_mul_i32 s4, s13, s28
	s_add_u32 s52, s4, s84
	s_addc_u32 s53, s5, s85
	v_cmp_gt_i64_e64 s[4:5], s[52:53], v[148:149]
	s_and_b64 vcc, exec, s[4:5]
	s_cbranch_vccnz .LBB0_897
	s_ashr_i32 s14, s52, 31
	s_lshr_b32 s14, s14, 29
	s_add_i32 s14, s52, s14
	s_ashr_i32 s15, s14, 3
	s_and_b32 s14, s14, -8
	s_sub_i32 s14, s52, s14
	s_cmp_lt_i32 s14, 0
	s_cselect_b32 s16, s9, 0x280
	s_mul_i32 s14, s14, s16
	s_add_i32 s14, s14, s15
	s_ashr_i32 s15, s14, 31
	s_lshr_b32 s15, s15, 25
	s_add_i32 s15, s14, s15
	s_ashr_i32 s16, s15, 7
	s_lshl_b32 s16, s16, 3
	s_and_b32 s15, s15, 0xffffff80
	s_sub_i32 s15, s14, s15
	s_ashr_i32 s14, s15, 3
	s_and_b32 s15, s15, 7
	s_add_i32 s26, s16, s15
	s_mov_b32 s23, 16
